# v33 + mid-epilogue wait counted (vmcnt(7): only the first old-XG load and the earlier stores) so the other seven loads stay in flight under the first compute
# speedup vs baseline: 1.0072x; 1.0059x over previous
; __host__ __device__ __forceinline__ unsigned img_off(unsigned row, unsigned col, unsigned KT) { return (((row >> 8) * KT + (col >> 6)) << 14) + (((row >> 7) & 1u) << 13) + hl_off(row & 127u, col & 63u); }
;     __device__ __forceinline__ void operator()(const f32x4 (&acc)[2][2][4][2], const Unit& u, int wr, int wc, int fr, int fq) const {
;     ...
;         bf16_t* gpb = XG + img_off((unsigned)(u.pm * BM + wr * 64 + fr), (unsigned)col0, 16u);
; #pragma unroll
;         for (int ai = 0; ai < 2; ++ai) {
;         u32x4 xin[2][4][2];
; #pragma unroll
;             for (int m = 0; m < 4; ++m)
; #pragma unroll
;                 for (int bj = 0; bj < 2; ++bj) xin[ai][m][bj] = *(const u32x4*)(gpb + ai * 8192 + m * 1024 + bj * 2 * 16384);
; #pragma unroll
;             for (int m = 0; m < 4; ++m) {
;                 const int row = u.pm * BM + ai * HALF + wr * 64 + m * 16 + fr;
;                 bf16_t* gp = gpb + ai * 8192 + m * 1024;
;                 float q = 0.f;
; #pragma unroll
;                 for (int bj = 0; bj < 2; ++bj) {
;                     const u32x4 xr = xin[ai][m][bj];
;                     f32x4 x0, x1;
;                     x0[0] = __builtin_bit_cast(float, xr.x << 16); x0[1] = __builtin_bit_cast(float, xr.x & 0xffff0000u); x0[2] = __builtin_bit_cast(float, xr.y << 16); x0[3] = __builtin_bit_cast(float, xr.y & 0xffff0000u);
;                     x1[0] = __builtin_bit_cast(float, xr.z << 16); x1[1] = __builtin_bit_cast(float, xr.z & 0xffff0000u); x1[2] = __builtin_bit_cast(float, xr.w << 16); x1[3] = __builtin_bit_cast(float, xr.w & 0xffff0000u);
.LBB0_257:
	s_or_b64 exec, exec, s[56:57]
	v_add_co_u32_e32 v148, vcc, 0x4000, v218
	s_nop 1
	v_addc_co_u32_e32 v149, vcc, 0, v219, vcc
	global_load_dwordx4 v[140:143], v[148:149], off
	v_add_co_u32_e32 v138, vcc, 0x14000, v218
	s_nop 1
	v_addc_co_u32_e32 v139, vcc, 0, v219, vcc
	global_load_dwordx4 v[144:147], v[138:139], off
	global_load_dwordx4 v[134:137], v[148:149], off offset:2048
	global_load_dwordx4 v[130:133], v[138:139], off offset:2048
	v_add_co_u32_e32 v114, vcc, 0x5000, v218
	s_waitcnt lgkmcnt(0)
	s_nop 0
	v_addc_co_u32_e32 v115, vcc, 0, v219, vcc
	v_add_co_u32_e32 v116, vcc, 0x15000, v218
	global_load_dwordx4 v[126:129], v[114:115], off
	s_nop 0
	v_addc_co_u32_e32 v117, vcc, 0, v219, vcc
	global_load_dwordx4 v[122:125], v[116:117], off
	global_load_dwordx4 v[118:121], v[114:115], off offset:2048
	s_nop 0
	global_load_dwordx4 v[114:117], v[116:117], off offset:2048
	s_waitcnt vmcnt(7)
	v_lshlrev_b32_e32 v150, 16, v140
	v_and_b32_e32 v151, 0xffff0000, v140


; __device__ __forceinline__ unsigned cvt_pk_bf16(float lo, float hi) { unsigned r; asm volatile("v_cvt_pk_bf16_f32 %0, %1, %2" : "=v"(r) : "v"(lo), "v"(hi)); return r; }
;     __device__ __forceinline__ void operator()(const f32x4 (&acc)[2][2][4][2], const Unit& u, int wr, int wc, int fr, int fq) const {
;     ...
;             for (int m = 0; m < 4; ++m) {
;                 const int row = u.pm * BM + ai * HALF + wr * 64 + m * 16 + fr;
;                 bf16_t* gp = gpb + ai * 8192 + m * 1024;
;                 float q = 0.f;
; #pragma unroll
;                 for (int bj = 0; bj < 2; ++bj) {
;                     const u32x4 xr = xin[ai][m][bj];
;                     f32x4 x0, x1;
;                     x0[0] = __builtin_bit_cast(float, xr.x << 16); x0[1] = __builtin_bit_cast(float, xr.x & 0xffff0000u); x0[2] = __builtin_bit_cast(float, xr.y << 16); x0[3] = __builtin_bit_cast(float, xr.y & 0xffff0000u);
;                     x1[0] = __builtin_bit_cast(float, xr.z << 16); x1[1] = __builtin_bit_cast(float, xr.z & 0xffff0000u); x1[2] = __builtin_bit_cast(float, xr.w << 16); x1[3] = __builtin_bit_cast(float, xr.w & 0xffff0000u);
;                     const f32x4 y0 = x0 * vr[bj][0] + vt[bj][0] * acc[ai][bj][m][0], y1 = x1 * vr[bj][1] + vt[bj][1] * acc[ai][bj][m][1];
;                     u32x4 w; w.x = cvt_pk_bf16(y0[0], y0[1]); w.y = cvt_pk_bf16(y0[2], y0[3]); w.z = cvt_pk_bf16(y1[0], y1[1]); w.w = cvt_pk_bf16(y1[2], y1[3]);
;                     *(u32x4*)(gp + bj * 2 * 16384) = w;
;                     const f32x4 z0 = y0 * vi[bj][0], z1 = y1 * vi[bj][1];
;                     q += (z0[0] * z0[0] + z0[1] * z0[1]) + (z0[2] * z0[2] + z0[3] * z0[3]) + (z1[0] * z1[0] + z1[1] * z1[1]) + (z1[2] * z1[2] + z1[3] * z1[3]);
;                 }
;                 q += __shfl_xor(q, 16); q += __shfl_xor(q, 32);
;                 if (fq == 0) ss[(size_t)row * 16 + u.pn * 4 + wc] = q;
	v_lshlrev_b32_e32 v140, 16, v141
	v_and_b32_e32 v141, 0xffff0000, v141
	v_lshlrev_b32_e32 v152, 16, v142
	v_and_b32_e32 v153, 0xffff0000, v142
	v_lshlrev_b32_e32 v142, 16, v143
	v_and_b32_e32 v143, 0xffff0000, v143
	v_pk_mul_f32 v[140:141], v[108:109], v[140:141]
	v_pk_mul_f32 v[150:151], v[106:107], v[150:151]
	v_pk_fma_f32 v[72:73], v[72:73], v[112:113], v[140:141]
	v_pk_mul_f32 v[140:141], v[98:99], v[152:153]
	v_pk_mul_f32 v[142:143], v[100:101], v[142:143]
	v_pk_fma_f32 v[70:71], v[70:71], v[110:111], v[150:151]
	v_pk_fma_f32 v[142:143], v[60:61], v[104:105], v[142:143]
	v_pk_fma_f32 v[140:141], v[58:59], v[102:103], v[140:141]
	v_cvt_pk_bf16_f32 v58, v70, v71
	v_cvt_pk_bf16_f32 v59, v72, v73
	s_nop 0
	v_cvt_pk_bf16_f32 v60, v140, v141
	v_cvt_pk_bf16_f32 v61, v142, v143
	global_store_dwordx4 v[148:149], v[58:61], off
	s_nop 1
	v_pk_mul_f32 v[58:59], v[96:97], v[72:73]
	v_pk_mul_f32 v[60:61], v[94:95], v[70:71]
	v_mul_f32_e32 v59, v59, v59
	v_mul_f32_e32 v61, v61, v61
	v_pk_mul_f32 v[72:73], v[90:91], v[140:141]
	v_fmac_f32_e32 v61, v60, v60
	v_fmac_f32_e32 v59, v58, v58
	v_add_f32_e32 v58, v61, v59
	v_mul_f32_e32 v59, v73, v73
	v_pk_mul_f32 v[70:71], v[92:93], v[142:143]
	v_fmac_f32_e32 v59, v72, v72
	v_add_f32_e32 v58, v59, v58
	v_mul_f32_e32 v59, v71, v71
	v_fmac_f32_e32 v59, v70, v70
	v_add_f32_e32 v140, v59, v58
	s_waitcnt vmcnt(7)
	v_lshlrev_b32_e32 v58, 16, v144
	v_and_b32_e32 v59, 0xffff0000, v144
	v_lshlrev_b32_e32 v60, 16, v145
	v_and_b32_e32 v61, 0xffff0000, v145
	v_lshlrev_b32_e32 v70, 16, v146
	v_and_b32_e32 v71, 0xffff0000, v146
	v_lshlrev_b32_e32 v72, 16, v147
	v_and_b32_e32 v73, 0xffff0000, v147
	v_pk_mul_f32 v[58:59], v[86:87], v[58:59]
	v_pk_mul_f32 v[60:61], v[88:89], v[60:61]
	v_pk_fma_f32 v[54:55], v[54:55], v[82:83], v[58:59]
	v_pk_fma_f32 v[56:57], v[56:57], v[84:85], v[60:61]
	v_pk_mul_f32 v[58:59], v[74:75], v[70:71]
	v_pk_mul_f32 v[60:61], v[76:77], v[72:73]
	v_pk_fma_f32 v[58:59], v[50:51], v[78:79], v[58:59]
	v_pk_fma_f32 v[60:61], v[52:53], v[80:81], v[60:61]
	v_cvt_pk_bf16_f32 v50, v54, v55
	v_cvt_pk_bf16_f32 v51, v56, v57
	v_cvt_pk_bf16_f32 v52, v58, v59
	s_nop 0
	v_cvt_pk_bf16_f32 v53, v60, v61
	global_store_dwordx4 v[138:139], v[50:53], off
	s_nop 1
	v_pk_mul_f32 v[50:51], v[68:69], v[56:57]
	v_pk_mul_f32 v[52:53], v[66:67], v[54:55]
	v_mul_f32_e32 v51, v51, v51
	v_mul_f32_e32 v53, v53, v53
	v_pk_mul_f32 v[56:57], v[62:63], v[58:59]
	v_fmac_f32_e32 v53, v52, v52
	v_fmac_f32_e32 v51, v50, v50
	v_add_f32_e32 v50, v53, v51
	v_mul_f32_e32 v51, v57, v57
	v_pk_mul_f32 v[54:55], v[64:65], v[60:61]
	v_fmac_f32_e32 v51, v56, v56
	v_add_f32_e32 v50, v51, v50
	v_mul_f32_e32 v51, v55, v55
	v_fmac_f32_e32 v51, v54, v54
	v_add_f32_e32 v50, v51, v50
	v_add_f32_e32 v50, v140, v50
	ds_bpermute_b32 v51, v162, v50
	s_waitcnt lgkmcnt(0)
	v_add_f32_e32 v50, v50, v51
	ds_bpermute_b32 v51, v163, v50
	s_and_saveexec_b64 s[56:57], s[38:39]
	s_cbranch_execz .LBB0_259
	v_add_u32_e32 v52, 0x80, v216
	v_ashrrev_i32_e32 v53, 31, v52
	v_readlane_b32 s28, v252, 39
	s_waitcnt lgkmcnt(0)
	v_add_f32_e32 v54, v50, v51
	v_lshlrev_b64 v[50:51], 6, v[52:53]
	v_readlane_b32 s29, v252, 40
	s_lshl_b32 s64, s76, 2
	s_nop 0
	v_lshl_add_u64 v[50:51], s[28:29], 0, v[50:51]
	v_lshl_add_u64 v[50:51], s[54:55], 2, v[50:51]
	v_lshl_add_u64 v[50:51], v[50:51], 0, s[64:65]
	global_store_dword v[50:51], v54, off

; __host__ __device__ __forceinline__ unsigned img_off(unsigned row, unsigned col, unsigned KT) { return (((row >> 8) * KT + (col >> 6)) << 14) + (((row >> 7) & 1u) << 13) + hl_off(row & 127u, col & 63u); }
;     __device__ __forceinline__ void operator()(const f32x4 (&acc)[2][2][4][2], const Unit& u, int wr, int wc, int fr, int fq) const {
;     ...
;         bf16_t* gpb = XG + img_off((unsigned)(u.pm * BM + wr * 64 + fr), (unsigned)col0, 16u);
; #pragma unroll
;         for (int ai = 0; ai < 2; ++ai) {
;         u32x4 xin[2][4][2];
; #pragma unroll
;             for (int m = 0; m < 4; ++m)
; #pragma unroll
;                 for (int bj = 0; bj < 2; ++bj) xin[ai][m][bj] = *(const u32x4*)(gpb + ai * 8192 + m * 1024 + bj * 2 * 16384);
; #pragma unroll
;             for (int m = 0; m < 4; ++m) {
;                 const int row = u.pm * BM + ai * HALF + wr * 64 + m * 16 + fr;
;                 bf16_t* gp = gpb + ai * 8192 + m * 1024;
;                 float q = 0.f;
; #pragma unroll
;                 for (int bj = 0; bj < 2; ++bj) {
;                     const u32x4 xr = xin[ai][m][bj];
;                     f32x4 x0, x1;
;                     x0[0] = __builtin_bit_cast(float, xr.x << 16); x0[1] = __builtin_bit_cast(float, xr.x & 0xffff0000u); x0[2] = __builtin_bit_cast(float, xr.y << 16); x0[3] = __builtin_bit_cast(float, xr.y & 0xffff0000u);
;                     x1[0] = __builtin_bit_cast(float, xr.z << 16); x1[1] = __builtin_bit_cast(float, xr.z & 0xffff0000u); x1[2] = __builtin_bit_cast(float, xr.w << 16); x1[3] = __builtin_bit_cast(float, xr.w & 0xffff0000u);
.LBB0_387:
	s_or_b64 exec, exec, s[54:55]
	v_add_co_u32_e32 v148, vcc, 0x4000, v218
	s_nop 1
	v_addc_co_u32_e32 v149, vcc, 0, v219, vcc
	global_load_dwordx4 v[140:143], v[148:149], off
	v_add_co_u32_e32 v138, vcc, 0x14000, v218
	s_nop 1
	v_addc_co_u32_e32 v139, vcc, 0, v219, vcc
	global_load_dwordx4 v[144:147], v[138:139], off
	global_load_dwordx4 v[134:137], v[148:149], off offset:2048
	global_load_dwordx4 v[130:133], v[138:139], off offset:2048
	v_add_co_u32_e32 v114, vcc, 0x5000, v218
	s_waitcnt lgkmcnt(0)
	s_nop 0
	v_addc_co_u32_e32 v115, vcc, 0, v219, vcc
	v_add_co_u32_e32 v116, vcc, 0x15000, v218
	global_load_dwordx4 v[126:129], v[114:115], off
	s_nop 0
	v_addc_co_u32_e32 v117, vcc, 0, v219, vcc
	global_load_dwordx4 v[122:125], v[116:117], off
	global_load_dwordx4 v[118:121], v[114:115], off offset:2048
	s_nop 0
	global_load_dwordx4 v[114:117], v[116:117], off offset:2048
	s_waitcnt vmcnt(7)
	v_lshlrev_b32_e32 v150, 16, v140
	v_and_b32_e32 v151, 0xffff0000, v140


; __device__ __forceinline__ unsigned cvt_pk_bf16(float lo, float hi) { unsigned r; asm volatile("v_cvt_pk_bf16_f32 %0, %1, %2" : "=v"(r) : "v"(lo), "v"(hi)); return r; }
;     __device__ __forceinline__ void operator()(const f32x4 (&acc)[2][2][4][2], const Unit& u, int wr, int wc, int fr, int fq) const {
;     ...
;             for (int m = 0; m < 4; ++m) {
;                 const int row = u.pm * BM + ai * HALF + wr * 64 + m * 16 + fr;
;                 bf16_t* gp = gpb + ai * 8192 + m * 1024;
;                 float q = 0.f;
; #pragma unroll
;                 for (int bj = 0; bj < 2; ++bj) {
;                     const u32x4 xr = xin[ai][m][bj];
;                     f32x4 x0, x1;
;                     x0[0] = __builtin_bit_cast(float, xr.x << 16); x0[1] = __builtin_bit_cast(float, xr.x & 0xffff0000u); x0[2] = __builtin_bit_cast(float, xr.y << 16); x0[3] = __builtin_bit_cast(float, xr.y & 0xffff0000u);
;                     x1[0] = __builtin_bit_cast(float, xr.z << 16); x1[1] = __builtin_bit_cast(float, xr.z & 0xffff0000u); x1[2] = __builtin_bit_cast(float, xr.w << 16); x1[3] = __builtin_bit_cast(float, xr.w & 0xffff0000u);
;                     const f32x4 y0 = x0 * vr[bj][0] + vt[bj][0] * acc[ai][bj][m][0], y1 = x1 * vr[bj][1] + vt[bj][1] * acc[ai][bj][m][1];
;                     u32x4 w; w.x = cvt_pk_bf16(y0[0], y0[1]); w.y = cvt_pk_bf16(y0[2], y0[3]); w.z = cvt_pk_bf16(y1[0], y1[1]); w.w = cvt_pk_bf16(y1[2], y1[3]);
;                     *(u32x4*)(gp + bj * 2 * 16384) = w;
;                     const f32x4 z0 = y0 * vi[bj][0], z1 = y1 * vi[bj][1];
;                     q += (z0[0] * z0[0] + z0[1] * z0[1]) + (z0[2] * z0[2] + z0[3] * z0[3]) + (z1[0] * z1[0] + z1[1] * z1[1]) + (z1[2] * z1[2] + z1[3] * z1[3]);
;                 }
;                 q += __shfl_xor(q, 16); q += __shfl_xor(q, 32);
;                 if (fq == 0) ss[(size_t)row * 16 + u.pn * 4 + wc] = q;
	v_lshlrev_b32_e32 v140, 16, v141
	v_and_b32_e32 v141, 0xffff0000, v141
	v_lshlrev_b32_e32 v152, 16, v142
	v_and_b32_e32 v153, 0xffff0000, v142
	v_lshlrev_b32_e32 v142, 16, v143
	v_and_b32_e32 v143, 0xffff0000, v143
	v_pk_mul_f32 v[140:141], v[108:109], v[140:141]
	v_pk_mul_f32 v[150:151], v[106:107], v[150:151]
	v_pk_fma_f32 v[72:73], v[72:73], v[112:113], v[140:141]
	v_pk_mul_f32 v[140:141], v[98:99], v[152:153]
	v_pk_mul_f32 v[142:143], v[100:101], v[142:143]
	v_pk_fma_f32 v[70:71], v[70:71], v[110:111], v[150:151]
	v_pk_fma_f32 v[142:143], v[60:61], v[104:105], v[142:143]
	v_pk_fma_f32 v[140:141], v[58:59], v[102:103], v[140:141]
	v_cvt_pk_bf16_f32 v58, v70, v71
	v_cvt_pk_bf16_f32 v59, v72, v73
	s_nop 0
	v_cvt_pk_bf16_f32 v60, v140, v141
	v_cvt_pk_bf16_f32 v61, v142, v143
	global_store_dwordx4 v[148:149], v[58:61], off
	s_nop 1
	v_pk_mul_f32 v[58:59], v[96:97], v[72:73]
	v_pk_mul_f32 v[60:61], v[94:95], v[70:71]
	v_mul_f32_e32 v59, v59, v59
	v_mul_f32_e32 v61, v61, v61
	v_pk_mul_f32 v[72:73], v[90:91], v[140:141]
	v_fmac_f32_e32 v61, v60, v60
	v_fmac_f32_e32 v59, v58, v58
	v_add_f32_e32 v58, v61, v59
	v_mul_f32_e32 v59, v73, v73
	v_pk_mul_f32 v[70:71], v[92:93], v[142:143]
	v_fmac_f32_e32 v59, v72, v72
	v_add_f32_e32 v58, v59, v58
	v_mul_f32_e32 v59, v71, v71
	v_fmac_f32_e32 v59, v70, v70
	v_add_f32_e32 v140, v59, v58
	s_waitcnt vmcnt(7)
	v_lshlrev_b32_e32 v58, 16, v144
	v_and_b32_e32 v59, 0xffff0000, v144
	v_lshlrev_b32_e32 v60, 16, v145
	v_and_b32_e32 v61, 0xffff0000, v145
	v_lshlrev_b32_e32 v70, 16, v146
	v_and_b32_e32 v71, 0xffff0000, v146
	v_lshlrev_b32_e32 v72, 16, v147
	v_and_b32_e32 v73, 0xffff0000, v147
	v_pk_mul_f32 v[58:59], v[86:87], v[58:59]
	v_pk_mul_f32 v[60:61], v[88:89], v[60:61]
	v_pk_fma_f32 v[54:55], v[54:55], v[82:83], v[58:59]
	v_pk_fma_f32 v[56:57], v[56:57], v[84:85], v[60:61]
	v_pk_mul_f32 v[58:59], v[74:75], v[70:71]
	v_pk_mul_f32 v[60:61], v[76:77], v[72:73]
	v_pk_fma_f32 v[58:59], v[50:51], v[78:79], v[58:59]
	v_pk_fma_f32 v[60:61], v[52:53], v[80:81], v[60:61]
	v_cvt_pk_bf16_f32 v50, v54, v55
	v_cvt_pk_bf16_f32 v51, v56, v57
	v_cvt_pk_bf16_f32 v52, v58, v59
	s_nop 0
	v_cvt_pk_bf16_f32 v53, v60, v61
	global_store_dwordx4 v[138:139], v[50:53], off
	s_nop 1
	v_pk_mul_f32 v[50:51], v[68:69], v[56:57]
	v_pk_mul_f32 v[52:53], v[66:67], v[54:55]
	v_mul_f32_e32 v51, v51, v51
	v_mul_f32_e32 v53, v53, v53
	v_pk_mul_f32 v[56:57], v[62:63], v[58:59]
	v_fmac_f32_e32 v53, v52, v52
	v_fmac_f32_e32 v51, v50, v50
	v_add_f32_e32 v50, v53, v51
	v_mul_f32_e32 v51, v57, v57
	v_pk_mul_f32 v[54:55], v[64:65], v[60:61]
	v_fmac_f32_e32 v51, v56, v56
	v_add_f32_e32 v50, v51, v50
	v_mul_f32_e32 v51, v55, v55
	v_fmac_f32_e32 v51, v54, v54
	v_add_f32_e32 v50, v51, v50
	v_add_f32_e32 v50, v140, v50
	ds_bpermute_b32 v51, v162, v50
	s_waitcnt lgkmcnt(0)
	v_add_f32_e32 v50, v50, v51
	ds_bpermute_b32 v51, v163, v50
	s_and_saveexec_b64 s[54:55], s[36:37]
	s_cbranch_execz .LBB0_389
	v_add_u32_e32 v52, 0x80, v216
	v_ashrrev_i32_e32 v53, 31, v52
	v_readlane_b32 s28, v252, 39
	s_waitcnt lgkmcnt(0)
	v_add_f32_e32 v54, v50, v51
	v_lshlrev_b64 v[50:51], 6, v[52:53]
	v_readlane_b32 s29, v252, 40
	s_lshl_b32 s62, s74, 2
	s_nop 0
	v_lshl_add_u64 v[50:51], s[28:29], 0, v[50:51]
	v_lshl_add_u64 v[50:51], s[52:53], 2, v[50:51]
	v_lshl_add_u64 v[50:51], v[50:51], 0, s[62:63]
	global_store_dword v[50:51], v54, off
